# P0: transpose-item waves run at raised priority next to the streaming RMSNorm waves
# speedup vs baseline: 1.0064x; 1.0064x over previous
.Lp0_tr:
	s_setprio 1
	s_lshl_b32 s2, s84, 14
	v_and_b32_e32 v9, 31, v230
	v_lshlrev_b32_e32 v1, 3, v230
	s_add_i32 s2, s2, 0
	v_lshlrev_b32_e32 v4, 2, v9
	v_mov_b32_e32 v5, 0
	v_lshrrev_b32_e32 v37, 3, v228
	v_and_b32_e32 v1, 56, v1
	v_lshl_add_u64 v[6:7], s[76:77], 0, v[4:5]
	v_add_u32_e32 v8, s2, v4
	v_mul_u32_u24_e32 v3, 0x84, v1
	v_lshlrev_b32_e32 v39, 2, v37
	v_lshl_add_u64 v[10:11], s[74:75], 0, v[4:5]
	v_lshl_add_u64 v[12:13], s[72:73], 0, v[4:5]
	v_lshl_add_u64 v[14:15], s[70:71], 0, v[4:5]
	v_lshl_add_u64 v[16:17], s[68:69], 0, v[4:5]
	v_lshl_add_u64 v[18:19], s[62:63], 0, v[4:5]
	v_lshl_add_u64 v[20:21], s[50:51], 0, v[4:5]
	v_lshlrev_b32_e32 v4, 1, v1
	v_add3_u32 v40, s2, v3, v39
	v_lshl_add_u64 v[22:23], s[10:11], 0, v[4:5]
	s_mov_b64 s[2:3], 0x2500000
	v_lshl_add_u64 v[24:25], v[22:23], 0, s[2:3]
	s_mov_b64 s[2:3], 0x1a00000
	v_lshl_add_u64 v[26:27], v[22:23], 0, s[2:3]
	s_mov_b64 s[2:3], 0x1800000
	v_lshl_add_u64 v[28:29], v[22:23], 0, s[2:3]
	s_mov_b64 s[2:3], 0x1500000
	v_lshrrev_b32_e32 v2, 5, v228
	v_bfe_u32 v38, v228, 3, 2
	v_lshl_add_u64 v[30:31], v[22:23], 0, s[2:3]
	s_mov_b64 s[2:3], 0x1300000
	s_mov_b32 s5, 0
	s_movk_i32 s14, 0x84
	v_or_b32_e32 v41, 8, v37
	v_or_b32_e32 v42, 16, v37
	v_or_b32_e32 v43, 24, v37
	v_and_b32_e32 v44, 16, v39
	v_lshl_add_u64 v[32:33], v[22:23], 0, s[2:3]
	v_or_b32_e32 v45, 0x800, v38
	v_or_b32_e32 v46, 0x400, v38
	v_mov_b32_e32 v1, v2
	s_movk_i32 s15, 0x1600
	s_movk_i32 s16, 0x63
	s_mov_b32 s17, 0x9800
	s_mov_b32 s18, s86
	s_branch .LBB0_9

.LBB0_53:
	s_cmp_eq_u32 s101, 2
	s_cbranch_scc1 .LBB0_71
	v_readlane_b32 s2, v254, 0
	s_setprio 0
	s_mov_b32 s4, 0x10000
	s_nop 0
	v_lshl_add_u32 v2, s2, 9, v230
	v_cmp_gt_i32_e32 vcc, s4, v2
	s_and_saveexec_b64 s[2:3], vcc
	v_readlane_b32 s16, v254, 11
	v_readlane_b32 s17, v254, 12
	s_cbranch_execz .LBB0_61
	v_cvt_f32_u32_e32 v1, s16
	v_add_u32_e32 v3, s16, v2
	v_mov_b32_e32 v4, s16
	v_cmp_gt_i32_e32 vcc, s4, v3
	v_rcp_iflag_f32_e32 v1, v1
	s_sub_i32 s12, 0, s16
	v_max_i32_e32 v5, 0x10000, v3
	v_addc_co_u32_e64 v4, s[4:5], v2, v4, vcc
	v_mul_f32_e32 v1, 0x4f7ffffe, v1
	v_cvt_u32_f32_e32 v1, v1
	v_sub_u32_e32 v4, v5, v4
	v_mul_lo_u32 v5, s12, v1
	v_mul_hi_u32 v5, v1, v5
	v_add_u32_e32 v1, v1, v5
	v_mul_hi_u32 v1, v4, v1
	v_mul_lo_u32 v5, v1, s16
	v_sub_u32_e32 v4, v4, v5
	v_add_u32_e32 v6, 1, v1
	v_cmp_le_u32_e64 s[4:5], s16, v4
	v_subrev_u32_e32 v5, s16, v4
	s_mov_b64 s[12:13], -1
	v_cndmask_b32_e64 v1, v1, v6, s[4:5]
	v_cndmask_b32_e64 v4, v4, v5, s[4:5]
	v_add_u32_e32 v5, 1, v1
	v_cmp_le_u32_e64 s[4:5], s16, v4
	s_nop 1
	v_cndmask_b32_e64 v1, v1, v5, s[4:5]
	v_addc_co_u32_e32 v1, vcc, 1, v1, vcc
	v_cmp_lt_u32_e32 vcc, 1, v1
	s_and_saveexec_b64 s[4:5], vcc
	s_cbranch_execz .LBB0_58
	s_add_u32 s12, s10, 0x12000000
	s_addc_u32 s13, s11, 0
	v_and_b32_e32 v6, -2, v1
	s_lshl_b32 s16, s92, 10
	s_mov_b32 s17, s16
	s_mov_b64 s[14:15], 0
	v_mov_b32_e32 v7, 0
	v_mov_b32_e32 v8, v6
	v_mov_b64_e32 v[4:5], v[2:3]

.Lp0_end:
	s_waitcnt lgkmcnt(0)
	s_setprio 0
	s_barrier
